# big-GEMM K loop: ring-index/counter updates moved in front of the k-step barrier (back-edge rotation)
# baseline (speedup 1.0000x reference)
; #define LDSR(dst, addr, off) asm volatile("ds_read_b128 %0, %1 offset:%2" : "=&v"(dst) : "v"(addr), "n"(off))
; #define LDSR(dst, addr, off) asm volatile("ds_read_b128 %0, %1 offset:%2" : "=&v"(dst) : "v"(addr), "n"(off))
; template <class AP, class BP, class Epi>
; DI void mfma_gemm_big_tile(const AP& aptr, const BP& bptr, int m0, int n0, int K, const Epi& epi, bf16* lds) {
;     ...
;   for (int ks = 0; ks < nk; ++ks) {
;     if (ks + 2 < nk) BG_ISSUE(nxt, ks + 2);
;     const unsigned sa = lbase + (unsigned)(cur * BG_STAGE * 2) + a_off, sb = lbase + (unsigned)(cur * BG_STAGE * 2) + b_off;
;     bf16x8 af[8], bfr[4];
;     LDSR(bfr[0], sb, 0); LDSR(bfr[1], sb, 1024); LDSR(bfr[2], sb, 2048); LDSR(bfr[3], sb, 3072);
;     LDSR(af[0], sa, 0); LDSR(af[1], sa, 1024); LDSR(af[2], sa, 2048); LDSR(af[3], sa, 3072);
;     LDSR(af[4], sa, 4096); LDSR(af[5], sa, 5120); LDSR(af[6], sa, 6144); LDSR(af[7], sa, 7168);
;     asm volatile("s_waitcnt lgkmcnt(0)" : "+v"(af[0]), "+v"(af[1]), "+v"(af[2]), "+v"(af[3]), "+v"(af[4]), "+v"(af[5]), "+v"(af[6]), "+v"(af[7]),
;                  "+v"(bfr[0]), "+v"(bfr[1]), "+v"(bfr[2]), "+v"(bfr[3]) : : "memory");
; #pragma unroll
;     for (int i = 0; i < 8; ++i)
; #pragma unroll
;       for (int j = 0; j < 4; ++j) acc[i][j] = __builtin_amdgcn_mfma_f32_16x16x32_bf16(bfr[j], af[i], acc[i][j], 0, 0, 0);
;     if (ks + 2 < nk) asm volatile("s_waitcnt vmcnt(6)\n\ts_barrier" ::: "memory");
;     else asm volatile("s_waitcnt vmcnt(0)\n\ts_barrier" ::: "memory");
;     cur = (cur == 2) ? 0 : cur + 1; nxt = (nxt == 2) ? 0 : nxt + 1;
.LBB0_249:
	s_cmpk_lg_i32 s0, 0x800
	s_cbranch_scc0 .LBB0_247

; template <class AP, class BP, class Epi>
; DI void mfma_gemm_big_tile(const AP& aptr, const BP& bptr, int m0, int n0, int K, const Epi& epi, bf16* lds) {
;     ...
; #pragma unroll
;     for (int i = 0; i < 8; ++i)
; #pragma unroll
;       for (int j = 0; j < 4; ++j) acc[i][j] = __builtin_amdgcn_mfma_f32_16x16x32_bf16(bfr[j], af[i], acc[i][j], 0, 0, 0);
;     if (ks + 2 < nk) asm volatile("s_waitcnt vmcnt(6)\n\ts_barrier" ::: "memory");
;     else asm volatile("s_waitcnt vmcnt(0)\n\ts_barrier" ::: "memory");
;     cur = (cur == 2) ? 0 : cur + 1; nxt = (nxt == 2) ? 0 : nxt + 1;
.LBB0_252:
	s_mov_b64 s[6:7], -1
	s_waitcnt lgkmcnt(7)
	s_and_b64 vcc, exec, s[4:5]
	v_mfma_f32_16x16x32_bf16 v[126:129], v[146:149], v[166:169], v[126:129]
	v_mfma_f32_16x16x32_bf16 v[122:125], v[150:153], v[166:169], v[122:125]
	v_mfma_f32_16x16x32_bf16 v[118:121], v[154:157], v[166:169], v[118:121]
	v_mfma_f32_16x16x32_bf16 v[114:117], v[162:165], v[166:169], v[114:117]
	s_waitcnt lgkmcnt(6)
	v_mfma_f32_16x16x32_bf16 v[110:113], v[146:149], v[182:185], v[110:113]
	v_mfma_f32_16x16x32_bf16 v[106:109], v[150:153], v[182:185], v[106:109]
	v_mfma_f32_16x16x32_bf16 v[102:105], v[154:157], v[182:185], v[102:105]
	v_mfma_f32_16x16x32_bf16 v[98:101], v[162:165], v[182:185], v[98:101]
	s_waitcnt lgkmcnt(5)
	v_mfma_f32_16x16x32_bf16 v[94:97], v[146:149], v[192:195], v[94:97]
	v_mfma_f32_16x16x32_bf16 v[90:93], v[150:153], v[192:195], v[90:93]
	v_mfma_f32_16x16x32_bf16 v[86:89], v[154:157], v[192:195], v[86:89]
	v_mfma_f32_16x16x32_bf16 v[82:85], v[162:165], v[192:195], v[82:85]
	s_waitcnt lgkmcnt(4)
	v_mfma_f32_16x16x32_bf16 v[78:81], v[146:149], v[196:199], v[78:81]
	v_mfma_f32_16x16x32_bf16 v[74:77], v[150:153], v[196:199], v[74:77]
	v_mfma_f32_16x16x32_bf16 v[70:73], v[154:157], v[196:199], v[70:73]
	v_mfma_f32_16x16x32_bf16 v[66:69], v[162:165], v[196:199], v[66:69]
	s_waitcnt lgkmcnt(3)
	v_mfma_f32_16x16x32_bf16 v[62:65], v[146:149], v[200:203], v[62:65]
	v_mfma_f32_16x16x32_bf16 v[58:61], v[150:153], v[200:203], v[58:61]
	v_mfma_f32_16x16x32_bf16 v[54:57], v[154:157], v[200:203], v[54:57]
	v_mfma_f32_16x16x32_bf16 v[50:53], v[162:165], v[200:203], v[50:53]
	s_waitcnt lgkmcnt(2)
	v_mfma_f32_16x16x32_bf16 v[46:49], v[146:149], v[204:207], v[46:49]
	v_mfma_f32_16x16x32_bf16 v[42:45], v[150:153], v[204:207], v[42:45]
	v_mfma_f32_16x16x32_bf16 v[38:41], v[154:157], v[204:207], v[38:41]
	v_mfma_f32_16x16x32_bf16 v[34:37], v[162:165], v[204:207], v[34:37]
	s_waitcnt lgkmcnt(1)
	v_mfma_f32_16x16x32_bf16 v[30:33], v[146:149], v[208:211], v[30:33]
	v_mfma_f32_16x16x32_bf16 v[26:29], v[150:153], v[208:211], v[26:29]
	v_mfma_f32_16x16x32_bf16 v[22:25], v[154:157], v[208:211], v[22:25]
	v_mfma_f32_16x16x32_bf16 v[18:21], v[162:165], v[208:211], v[18:21]
	s_waitcnt lgkmcnt(0)
	v_mfma_f32_16x16x32_bf16 v[14:17], v[146:149], v[212:215], v[14:17]
	v_mfma_f32_16x16x32_bf16 v[10:13], v[150:153], v[212:215], v[10:13]
	v_mfma_f32_16x16x32_bf16 v[6:9], v[154:157], v[212:215], v[6:9]
	v_mfma_f32_16x16x32_bf16 v[2:5], v[162:165], v[212:215], v[2:5]
	s_add_i32 s4, s19, 1
	s_cmp_lg_u32 s19, 2
	s_cselect_b32 s19, s4, 0
	s_add_i32 s4, s13, 1
	s_cmp_lg_u32 s13, 2
	s_cselect_b32 s13, s4, 0
	s_add_i32 s16, s16, 1
	s_add_u32 s0, s0, 64
	s_addc_u32 s1, s1, 0
	s_cbranch_vccz .LBB0_254
	s_waitcnt vmcnt(0)
	s_barrier
	s_mov_b64 s[6:7], 0

; template <class AP, class BP, class Epi>
; DI void mfma_gemm_big_tile(const AP& aptr, const BP& bptr, int m0, int n0, int K, const Epi& epi, bf16* lds) {
;     ...
; #pragma unroll
;     for (int i = 0; i < 8; ++i)
; #pragma unroll
;       for (int j = 0; j < 4; ++j) acc[i][j] = __builtin_amdgcn_mfma_f32_16x16x32_bf16(bfr[j], af[i], acc[i][j], 0, 0, 0);
;     if (ks + 2 < nk) asm volatile("s_waitcnt vmcnt(6)\n\ts_barrier" ::: "memory");
;     else asm volatile("s_waitcnt vmcnt(0)\n\ts_barrier" ::: "memory");
;     cur = (cur == 2) ? 0 : cur + 1; nxt = (nxt == 2) ? 0 : nxt + 1;
.LBB0_512:
	s_mov_b64 s[6:7], -1
	s_waitcnt lgkmcnt(7)
	s_and_b64 vcc, exec, s[4:5]
	v_mfma_f32_16x16x32_bf16 v[126:129], v[146:149], v[166:169], v[126:129]
	v_mfma_f32_16x16x32_bf16 v[122:125], v[150:153], v[166:169], v[122:125]
	v_mfma_f32_16x16x32_bf16 v[118:121], v[154:157], v[166:169], v[118:121]
	v_mfma_f32_16x16x32_bf16 v[114:117], v[162:165], v[166:169], v[114:117]
	s_waitcnt lgkmcnt(6)
	v_mfma_f32_16x16x32_bf16 v[110:113], v[146:149], v[192:195], v[110:113]
	v_mfma_f32_16x16x32_bf16 v[106:109], v[150:153], v[192:195], v[106:109]
	v_mfma_f32_16x16x32_bf16 v[102:105], v[154:157], v[192:195], v[102:105]
	v_mfma_f32_16x16x32_bf16 v[98:101], v[162:165], v[192:195], v[98:101]
	s_waitcnt lgkmcnt(5)
	v_mfma_f32_16x16x32_bf16 v[94:97], v[146:149], v[196:199], v[94:97]
	v_mfma_f32_16x16x32_bf16 v[90:93], v[150:153], v[196:199], v[90:93]
	v_mfma_f32_16x16x32_bf16 v[86:89], v[154:157], v[196:199], v[86:89]
	v_mfma_f32_16x16x32_bf16 v[82:85], v[162:165], v[196:199], v[82:85]
	s_waitcnt lgkmcnt(4)
	v_mfma_f32_16x16x32_bf16 v[78:81], v[146:149], v[200:203], v[78:81]
	v_mfma_f32_16x16x32_bf16 v[74:77], v[150:153], v[200:203], v[74:77]
	v_mfma_f32_16x16x32_bf16 v[70:73], v[154:157], v[200:203], v[70:73]
	v_mfma_f32_16x16x32_bf16 v[66:69], v[162:165], v[200:203], v[66:69]
	s_waitcnt lgkmcnt(3)
	v_mfma_f32_16x16x32_bf16 v[62:65], v[146:149], v[204:207], v[62:65]
	v_mfma_f32_16x16x32_bf16 v[58:61], v[150:153], v[204:207], v[58:61]
	v_mfma_f32_16x16x32_bf16 v[54:57], v[154:157], v[204:207], v[54:57]
	v_mfma_f32_16x16x32_bf16 v[50:53], v[162:165], v[204:207], v[50:53]
	s_waitcnt lgkmcnt(2)
	v_mfma_f32_16x16x32_bf16 v[46:49], v[146:149], v[208:211], v[46:49]
	v_mfma_f32_16x16x32_bf16 v[42:45], v[150:153], v[208:211], v[42:45]
	v_mfma_f32_16x16x32_bf16 v[38:41], v[154:157], v[208:211], v[38:41]
	v_mfma_f32_16x16x32_bf16 v[34:37], v[162:165], v[208:211], v[34:37]
	s_waitcnt lgkmcnt(1)
	v_mfma_f32_16x16x32_bf16 v[30:33], v[146:149], v[212:215], v[30:33]
	v_mfma_f32_16x16x32_bf16 v[26:29], v[150:153], v[212:215], v[26:29]
	v_mfma_f32_16x16x32_bf16 v[22:25], v[154:157], v[212:215], v[22:25]
	v_mfma_f32_16x16x32_bf16 v[18:21], v[162:165], v[212:215], v[18:21]
	s_waitcnt lgkmcnt(0)
	v_mfma_f32_16x16x32_bf16 v[14:17], v[146:149], v[216:219], v[14:17]
	v_mfma_f32_16x16x32_bf16 v[10:13], v[150:153], v[216:219], v[10:13]
	v_mfma_f32_16x16x32_bf16 v[6:9], v[154:157], v[216:219], v[6:9]
	v_mfma_f32_16x16x32_bf16 v[2:5], v[162:165], v[216:219], v[2:5]
	s_add_i32 s4, s18, 1
	s_cmp_lg_u32 s18, 2
	s_cselect_b32 s18, s4, 0
	s_add_i32 s4, s13, 1
	s_cmp_lg_u32 s13, 2
	s_cselect_b32 s13, s4, 0
	s_add_i32 s15, s15, 1
	s_add_u32 s0, s0, 64
	s_addc_u32 s1, s1, 0
	s_cbranch_vccz .LBB0_514
	s_waitcnt vmcnt(0)
	s_barrier
	s_mov_b64 s[6:7], 0

; #define LDSR(dst, addr, off) asm volatile("ds_read_b128 %0, %1 offset:%2" : "=&v"(dst) : "v"(addr), "n"(off))
; #define LDSR(dst, addr, off) asm volatile("ds_read_b128 %0, %1 offset:%2" : "=&v"(dst) : "v"(addr), "n"(off))
; template <class AP, class BP, class Epi>
; DI void mfma_gemm_big_tile(const AP& aptr, const BP& bptr, int m0, int n0, int K, const Epi& epi, bf16* lds) {
;     ...
;   for (int ks = 0; ks < nk; ++ks) {
;     if (ks + 2 < nk) BG_ISSUE(nxt, ks + 2);
;     const unsigned sa = lbase + (unsigned)(cur * BG_STAGE * 2) + a_off, sb = lbase + (unsigned)(cur * BG_STAGE * 2) + b_off;
;     bf16x8 af[8], bfr[4];
;     LDSR(bfr[0], sb, 0); LDSR(bfr[1], sb, 1024); LDSR(bfr[2], sb, 2048); LDSR(bfr[3], sb, 3072);
;     LDSR(af[0], sa, 0); LDSR(af[1], sa, 1024); LDSR(af[2], sa, 2048); LDSR(af[3], sa, 3072);
;     LDSR(af[4], sa, 4096); LDSR(af[5], sa, 5120); LDSR(af[6], sa, 6144); LDSR(af[7], sa, 7168);
;     asm volatile("s_waitcnt lgkmcnt(0)" : "+v"(af[0]), "+v"(af[1]), "+v"(af[2]), "+v"(af[3]), "+v"(af[4]), "+v"(af[5]), "+v"(af[6]), "+v"(af[7]),
;                  "+v"(bfr[0]), "+v"(bfr[1]), "+v"(bfr[2]), "+v"(bfr[3]) : : "memory");
; #pragma unroll
;     for (int i = 0; i < 8; ++i)
; #pragma unroll
;       for (int j = 0; j < 4; ++j) acc[i][j] = __builtin_amdgcn_mfma_f32_16x16x32_bf16(bfr[j], af[i], acc[i][j], 0, 0, 0);
;     if (ks + 2 < nk) asm volatile("s_waitcnt vmcnt(6)\n\ts_barrier" ::: "memory");
;     else asm volatile("s_waitcnt vmcnt(0)\n\ts_barrier" ::: "memory");
;     cur = (cur == 2) ? 0 : cur + 1; nxt = (nxt == 2) ? 0 : nxt + 1;
.LBB0_1106:
	s_cmpk_eq_i32 s0, 0x800
	s_cbranch_scc1 .LBB0_1104

; template <class AP, class BP, class Epi>
; DI void mfma_gemm_big_tile(const AP& aptr, const BP& bptr, int m0, int n0, int K, const Epi& epi, bf16* lds) {
;     ...
; #pragma unroll
;     for (int i = 0; i < 8; ++i)
; #pragma unroll
;       for (int j = 0; j < 4; ++j) acc[i][j] = __builtin_amdgcn_mfma_f32_16x16x32_bf16(bfr[j], af[i], acc[i][j], 0, 0, 0);
;     if (ks + 2 < nk) asm volatile("s_waitcnt vmcnt(6)\n\ts_barrier" ::: "memory");
;     else asm volatile("s_waitcnt vmcnt(0)\n\ts_barrier" ::: "memory");
;     cur = (cur == 2) ? 0 : cur + 1; nxt = (nxt == 2) ? 0 : nxt + 1;
.LBB0_1109:
	s_mov_b64 s[10:11], -1
	s_waitcnt lgkmcnt(7)
	s_and_b64 vcc, exec, s[8:9]
	v_mfma_f32_16x16x32_bf16 v[126:129], v[146:149], v[166:169], v[126:129]
	v_mfma_f32_16x16x32_bf16 v[122:125], v[150:153], v[166:169], v[122:125]
	v_mfma_f32_16x16x32_bf16 v[118:121], v[154:157], v[166:169], v[118:121]
	v_mfma_f32_16x16x32_bf16 v[114:117], v[162:165], v[166:169], v[114:117]
	s_waitcnt lgkmcnt(6)
	v_mfma_f32_16x16x32_bf16 v[110:113], v[146:149], v[182:185], v[110:113]
	v_mfma_f32_16x16x32_bf16 v[106:109], v[150:153], v[182:185], v[106:109]
	v_mfma_f32_16x16x32_bf16 v[102:105], v[154:157], v[182:185], v[102:105]
	v_mfma_f32_16x16x32_bf16 v[98:101], v[162:165], v[182:185], v[98:101]
	s_waitcnt lgkmcnt(5)
	v_mfma_f32_16x16x32_bf16 v[94:97], v[146:149], v[192:195], v[94:97]
	v_mfma_f32_16x16x32_bf16 v[90:93], v[150:153], v[192:195], v[90:93]
	v_mfma_f32_16x16x32_bf16 v[86:89], v[154:157], v[192:195], v[86:89]
	v_mfma_f32_16x16x32_bf16 v[82:85], v[162:165], v[192:195], v[82:85]
	s_waitcnt lgkmcnt(4)
	v_mfma_f32_16x16x32_bf16 v[78:81], v[146:149], v[196:199], v[78:81]
	v_mfma_f32_16x16x32_bf16 v[74:77], v[150:153], v[196:199], v[74:77]
	v_mfma_f32_16x16x32_bf16 v[70:73], v[154:157], v[196:199], v[70:73]
	v_mfma_f32_16x16x32_bf16 v[66:69], v[162:165], v[196:199], v[66:69]
	s_waitcnt lgkmcnt(3)
	v_mfma_f32_16x16x32_bf16 v[62:65], v[146:149], v[200:203], v[62:65]
	v_mfma_f32_16x16x32_bf16 v[58:61], v[150:153], v[200:203], v[58:61]
	v_mfma_f32_16x16x32_bf16 v[54:57], v[154:157], v[200:203], v[54:57]
	v_mfma_f32_16x16x32_bf16 v[50:53], v[162:165], v[200:203], v[50:53]
	s_waitcnt lgkmcnt(2)
	v_mfma_f32_16x16x32_bf16 v[46:49], v[146:149], v[204:207], v[46:49]
	v_mfma_f32_16x16x32_bf16 v[42:45], v[150:153], v[204:207], v[42:45]
	v_mfma_f32_16x16x32_bf16 v[38:41], v[154:157], v[204:207], v[38:41]
	v_mfma_f32_16x16x32_bf16 v[34:37], v[162:165], v[204:207], v[34:37]
	s_waitcnt lgkmcnt(1)
	v_mfma_f32_16x16x32_bf16 v[30:33], v[146:149], v[208:211], v[30:33]
	v_mfma_f32_16x16x32_bf16 v[26:29], v[150:153], v[208:211], v[26:29]
	v_mfma_f32_16x16x32_bf16 v[22:25], v[154:157], v[208:211], v[22:25]
	v_mfma_f32_16x16x32_bf16 v[18:21], v[162:165], v[208:211], v[18:21]
	s_waitcnt lgkmcnt(0)
	v_mfma_f32_16x16x32_bf16 v[14:17], v[146:149], v[212:215], v[14:17]
	v_mfma_f32_16x16x32_bf16 v[10:13], v[150:153], v[212:215], v[10:13]
	v_mfma_f32_16x16x32_bf16 v[6:9], v[154:157], v[212:215], v[6:9]
	v_mfma_f32_16x16x32_bf16 v[2:5], v[162:165], v[212:215], v[2:5]
	s_add_i32 s8, s21, 1
	s_cmp_lg_u32 s21, 2
	s_cselect_b32 s21, s8, 0
	s_add_i32 s8, s17, 1
	s_cmp_lg_u32 s17, 2
	s_cselect_b32 s17, s8, 0
	s_add_i32 s18, s18, 1
	s_add_u32 s0, s0, 64
	s_addc_u32 s1, s1, 0
	s_cbranch_vccz .LBB0_1111
	s_waitcnt vmcnt(0)
	s_barrier
	s_mov_b64 s[10:11], 0
